# v56 plus GLU epilogue: all sixteen YG multiplicand reads requested at the top with counted waits (edit_glu_pref)
# speedup vs baseline: 1.0018x; 1.0018x over previous
.LBB0_385:
	s_and_b64 s[4:5], s[6:7], exec
	s_cselect_b32 s0, 0x100, 0
	v_or_b32_e32 v58, s0, v78
	v_or_b32_e32 v60, s26, v58
	v_readlane_b32 s4, v242, 16
	v_lshlrev_b32_e32 v62, 2, v60
	v_readlane_b32 s12, v242, 24
	v_readlane_b32 s13, v242, 25
	s_nop 4
	global_load_dwordx4 v[74:77], v62, s[12:13] offset:16
	global_load_dwordx4 v[78:81], v62, s[12:13]
	v_add_u32_e32 v148, s99, v1
	v_ashrrev_i32_e32 v149, 31, v148
	v_lshlrev_b64 v[58:59], 10, v[148:149]
	v_lshl_add_u64 v[58:59], s[80:81], 0, v[58:59]
	v_lshlrev_b32_e32 v146, 1, v60
	v_mov_b32_e32 v147, 0
	v_lshl_add_u64 v[154:155], v[58:59], 0, v[146:147]
	global_load_dwordx4 v[150:153], v[154:155], off
	global_load_dwordx4 v[58:61], v62, s[12:13] offset:528
	s_nop 0
	global_load_dwordx4 v[62:65], v62, s[12:13] offset:512
	global_load_dwordx4 v[164:167], v[154:155], off offset:256
	s_mov_b32 s100, 0x4000
	s_mov_b32 s101, 0
	v_lshl_add_u64 v[228:229], s[100:101], 0, v[154:155]
	global_load_dwordx4 v[168:171], v[228:229], off
	global_load_dwordx4 v[172:175], v[228:229], off offset:256
	s_mov_b32 s100, 0x8000
	s_mov_b32 s101, 0
	v_lshl_add_u64 v[228:229], s[100:101], 0, v[154:155]
	global_load_dwordx4 v[176:179], v[228:229], off
	global_load_dwordx4 v[180:183], v[228:229], off offset:256
	s_mov_b32 s100, 0xfc568000
	s_mov_b32 s101, -1
	v_lshl_add_u64 v[228:229], s[100:101], 0, v[154:155]
	global_load_dwordx4 v[184:187], v[228:229], off
	global_load_dwordx4 v[188:191], v[228:229], off offset:256
	s_mov_b32 s100, 0x18000
	s_mov_b32 s101, 0
	v_lshl_add_u64 v[228:229], s[100:101], 0, v[154:155]
	global_load_dwordx4 v[192:195], v[228:229], off
	global_load_dwordx4 v[196:199], v[228:229], off offset:256
	s_mov_b32 s100, 0x1c000
	s_mov_b32 s101, 0
	v_lshl_add_u64 v[228:229], s[100:101], 0, v[154:155]
	global_load_dwordx4 v[200:203], v[228:229], off
	global_load_dwordx4 v[204:207], v[228:229], off offset:256
	s_mov_b32 s100, 0x20000
	s_mov_b32 s101, 0
	v_lshl_add_u64 v[228:229], s[100:101], 0, v[154:155]
	global_load_dwordx4 v[208:211], v[228:229], off
	global_load_dwordx4 v[216:219], v[228:229], off offset:256
	s_mov_b32 s100, 0xfc568000
	s_mov_b32 s101, -1
	v_lshl_add_u64 v[228:229], s[100:101], 0, v[154:155]
	global_load_dwordx4 v[220:223], v[228:229], off
	global_load_dwordx4 v[224:227], v[228:229], off offset:256
	v_readlane_b32 s5, v242, 17
	v_readlane_b32 s6, v242, 18
	v_readlane_b32 s7, v242, 19
	v_readlane_b32 s8, v242, 20
	v_readlane_b32 s9, v242, 21
	v_readlane_b32 s10, v242, 22
	v_readlane_b32 s11, v242, 23
	v_readlane_b32 s14, v242, 26
	v_readlane_b32 s15, v242, 27
	v_readlane_b32 s16, v242, 28
	v_readlane_b32 s17, v242, 29
	v_readlane_b32 s18, v242, 30
	v_readlane_b32 s19, v242, 31
	s_waitcnt vmcnt(15)
	v_add_f32_e32 v138, v138, v74
	v_add_f32_e32 v1, v142, v78
	v_add_f32_e32 v142, v143, v79
	v_add_f32_e32 v139, v139, v75
	v_add_f32_e32 v143, v144, v80
	v_add_f32_e32 v140, v140, v76
	v_add_f32_e32 v144, v145, v81
	v_add_f32_e32 v141, v141, v77
	v_mul_f32_e32 v1, 0xbfb8aa3b, v1
	v_mul_f32_e32 v138, 0xbfb8aa3b, v138
	v_mul_f32_e32 v142, 0xbfb8aa3b, v142
	v_mul_f32_e32 v139, 0xbfb8aa3b, v139
	v_mul_f32_e32 v143, 0xbfb8aa3b, v143
	v_mul_f32_e32 v140, 0xbfb8aa3b, v140
	v_mul_f32_e32 v144, 0xbfb8aa3b, v144
	v_mul_f32_e32 v141, 0xbfb8aa3b, v141
	v_exp_f32_e32 v1, v1
	v_exp_f32_e32 v138, v138
	v_exp_f32_e32 v142, v142
	v_exp_f32_e32 v139, v139
	v_exp_f32_e32 v143, v143
	v_exp_f32_e32 v140, v140
	v_exp_f32_e32 v144, v144
	v_exp_f32_e32 v141, v141
	v_add_f32_e32 v1, 1.0, v1
	v_add_f32_e32 v138, 1.0, v138
	v_add_f32_e32 v142, 1.0, v142
	v_add_f32_e32 v139, 1.0, v139
	v_add_f32_e32 v143, 1.0, v143
	v_add_f32_e32 v140, 1.0, v140
	v_add_f32_e32 v144, 1.0, v144
	v_add_f32_e32 v141, 1.0, v141
	v_rcp_f32_e32 v1, v1
	v_rcp_f32_e32 v138, v138
	v_rcp_f32_e32 v142, v142
	v_rcp_f32_e32 v139, v139
	v_rcp_f32_e32 v143, v143
	v_rcp_f32_e32 v140, v140
	v_rcp_f32_e32 v144, v144
	v_rcp_f32_e32 v141, v141
	v_lshlrev_b32_e32 v145, 16, v150
	v_and_b32_e32 v150, 0xffff0000, v150
	v_lshlrev_b32_e32 v156, 16, v151
	v_and_b32_e32 v151, 0xffff0000, v151
	v_lshlrev_b32_e32 v157, 16, v152
	v_and_b32_e32 v152, 0xffff0000, v152
	v_lshlrev_b32_e32 v158, 16, v153
	v_and_b32_e32 v153, 0xffff0000, v153
	v_mul_f32_e32 v1, v1, v145
	v_mul_f32_e32 v145, v138, v157
	v_mul_f32_e32 v138, v142, v150
	v_mul_f32_e32 v142, v139, v152
	v_mul_f32_e32 v139, v143, v156
	v_mul_f32_e32 v143, v140, v158
	v_mul_f32_e32 v140, v144, v151
	v_mul_f32_e32 v141, v141, v153
	v_cvt_pk_bf16_f32 v138, v1, v138
	v_cvt_pk_bf16_f32 v139, v139, v140
	v_cvt_pk_bf16_f32 v140, v145, v142
	v_cvt_pk_bf16_f32 v141, v143, v141
	v_add_f32_e32 v1, v134, v62
	v_add_f32_e32 v130, v130, v58
	v_add_f32_e32 v134, v135, v63
	v_add_f32_e32 v131, v131, v59
	v_add_f32_e32 v135, v136, v64
	v_add_f32_e32 v132, v132, v60
	v_add_f32_e32 v136, v137, v65
	v_add_f32_e32 v133, v133, v61
	v_mul_f32_e32 v1, 0xbfb8aa3b, v1
	v_mul_f32_e32 v130, 0xbfb8aa3b, v130
	v_mul_f32_e32 v134, 0xbfb8aa3b, v134
	v_mul_f32_e32 v131, 0xbfb8aa3b, v131
	v_mul_f32_e32 v135, 0xbfb8aa3b, v135
	v_mul_f32_e32 v132, 0xbfb8aa3b, v132
	v_mul_f32_e32 v136, 0xbfb8aa3b, v136
	v_mul_f32_e32 v133, 0xbfb8aa3b, v133
	v_exp_f32_e32 v1, v1
	v_exp_f32_e32 v130, v130
	v_exp_f32_e32 v134, v134
	v_exp_f32_e32 v131, v131
	v_exp_f32_e32 v135, v135
	v_exp_f32_e32 v132, v132
	v_exp_f32_e32 v136, v136
	v_exp_f32_e32 v133, v133
	v_add_f32_e32 v1, 1.0, v1
	v_add_f32_e32 v130, 1.0, v130
	v_add_f32_e32 v134, 1.0, v134
	v_add_f32_e32 v131, 1.0, v131
	v_add_f32_e32 v135, 1.0, v135
	v_add_f32_e32 v132, 1.0, v132
	v_add_f32_e32 v136, 1.0, v136
	v_add_f32_e32 v133, 1.0, v133
	v_add_u32_e32 v150, 16, v148
	v_lshlrev_b64 v[152:153], 11, v[148:149]
	v_rcp_f32_e32 v1, v1
	v_rcp_f32_e32 v130, v130
	v_rcp_f32_e32 v134, v134
	v_rcp_f32_e32 v131, v131
	v_rcp_f32_e32 v135, v135
	v_rcp_f32_e32 v132, v132
	v_rcp_f32_e32 v136, v136
	v_rcp_f32_e32 v133, v133
	v_ashrrev_i32_e32 v151, 31, v150
	v_lshl_add_u64 v[152:153], s[60:61], 0, v[152:153]
	v_lshlrev_b64 v[154:155], 10, v[150:151]
	v_lshl_add_u64 v[152:153], v[152:153], 0, v[146:147]
	v_lshl_add_u64 v[154:155], s[80:81], 0, v[154:155]
	global_store_dwordx4 v[152:153], v[138:141], off offset:1024
	v_lshl_add_u64 v[154:155], v[154:155], 0, v[146:147]
	v_add_f32_e32 v122, v122, v74
	v_add_f32_e32 v123, v123, v75
	v_add_f32_e32 v124, v124, v76
	v_add_f32_e32 v125, v125, v77
	v_mul_f32_e32 v122, 0xbfb8aa3b, v122
	v_mul_f32_e32 v123, 0xbfb8aa3b, v123
	v_mul_f32_e32 v124, 0xbfb8aa3b, v124
	v_mul_f32_e32 v125, 0xbfb8aa3b, v125
	v_exp_f32_e32 v122, v122
	v_exp_f32_e32 v123, v123
	v_exp_f32_e32 v124, v124
	v_exp_f32_e32 v125, v125
	v_add_f32_e32 v122, 1.0, v122
	v_add_f32_e32 v123, 1.0, v123
	v_add_f32_e32 v124, 1.0, v124
	v_add_f32_e32 v125, 1.0, v125
	v_rcp_f32_e32 v122, v122
	v_rcp_f32_e32 v123, v123
	v_rcp_f32_e32 v124, v124
	v_rcp_f32_e32 v125, v125
	v_add_f32_e32 v114, v114, v58
	v_add_f32_e32 v115, v115, v59
	v_add_f32_e32 v116, v116, v60
	v_add_f32_e32 v117, v117, v61
	v_mul_f32_e32 v114, 0xbfb8aa3b, v114
	v_mul_f32_e32 v115, 0xbfb8aa3b, v115
	v_mul_f32_e32 v116, 0xbfb8aa3b, v116
	v_mul_f32_e32 v117, 0xbfb8aa3b, v117
	v_exp_f32_e32 v114, v114
	v_exp_f32_e32 v115, v115
	s_waitcnt vmcnt(15)
	v_mov_b32_e32 v142, v164
	v_mov_b32_e32 v143, v165
	v_mov_b32_e32 v144, v166
	v_mov_b32_e32 v145, v167
	v_lshlrev_b32_e32 v137, 16, v142
	v_and_b32_e32 v138, 0xffff0000, v142
	v_lshlrev_b32_e32 v139, 16, v143
	v_and_b32_e32 v140, 0xffff0000, v143
	v_lshlrev_b32_e32 v141, 16, v144
	v_and_b32_e32 v142, 0xffff0000, v144
	v_lshlrev_b32_e32 v143, 16, v145
	v_and_b32_e32 v144, 0xffff0000, v145
	v_mul_f32_e32 v1, v1, v137
	v_mul_f32_e32 v137, v130, v141
	v_mul_f32_e32 v130, v134, v138
	v_mul_f32_e32 v134, v131, v142
	v_mul_f32_e32 v131, v135, v139
	v_mul_f32_e32 v135, v132, v143
	v_mul_f32_e32 v132, v136, v140
	v_mul_f32_e32 v133, v133, v144
	v_cvt_pk_bf16_f32 v130, v1, v130
	v_cvt_pk_bf16_f32 v131, v131, v132
	v_cvt_pk_bf16_f32 v132, v137, v134
	v_cvt_pk_bf16_f32 v133, v135, v133
	v_add_f32_e32 v1, v126, v78
	v_add_f32_e32 v126, v127, v79
	v_add_f32_e32 v127, v128, v80
	v_add_f32_e32 v128, v129, v81
	v_mul_f32_e32 v1, 0xbfb8aa3b, v1
	v_mul_f32_e32 v126, 0xbfb8aa3b, v126
	v_mul_f32_e32 v127, 0xbfb8aa3b, v127
	v_mul_f32_e32 v128, 0xbfb8aa3b, v128
	v_exp_f32_e32 v1, v1
	v_exp_f32_e32 v126, v126
	v_exp_f32_e32 v127, v127
	v_exp_f32_e32 v128, v128
	v_add_f32_e32 v1, 1.0, v1
	v_add_f32_e32 v126, 1.0, v126
	v_add_f32_e32 v127, 1.0, v127
	v_add_f32_e32 v128, 1.0, v128
	v_rcp_f32_e32 v1, v1
	v_rcp_f32_e32 v126, v126
	v_rcp_f32_e32 v127, v127
	v_rcp_f32_e32 v128, v128
	global_store_dwordx4 v[152:153], v[130:133], off offset:1280
	v_exp_f32_e32 v116, v116
	v_exp_f32_e32 v117, v117
	v_add_f32_e32 v114, 1.0, v114
	v_add_f32_e32 v115, 1.0, v115
	v_add_f32_e32 v116, 1.0, v116
	v_add_f32_e32 v117, 1.0, v117
	v_rcp_f32_e32 v114, v114
	v_rcp_f32_e32 v115, v115
	v_rcp_f32_e32 v116, v116
	v_rcp_f32_e32 v117, v117
	v_add_f32_e32 v106, v106, v74
	v_add_f32_e32 v107, v107, v75
	v_add_f32_e32 v108, v108, v76
	v_add_f32_e32 v109, v109, v77
	v_mul_f32_e32 v106, 0xbfb8aa3b, v106
	v_mul_f32_e32 v107, 0xbfb8aa3b, v107
	v_mul_f32_e32 v108, 0xbfb8aa3b, v108
	v_mul_f32_e32 v109, 0xbfb8aa3b, v109
	v_exp_f32_e32 v106, v106
	v_exp_f32_e32 v107, v107
	v_exp_f32_e32 v108, v108
	v_exp_f32_e32 v109, v109
	v_add_f32_e32 v106, 1.0, v106
	v_add_f32_e32 v107, 1.0, v107
	v_add_f32_e32 v108, 1.0, v108
	v_add_f32_e32 v109, 1.0, v109
	v_rcp_f32_e32 v106, v106
	v_rcp_f32_e32 v107, v107
	v_rcp_f32_e32 v108, v108
	v_rcp_f32_e32 v109, v109
	v_add_f32_e32 v98, v98, v58
	v_add_f32_e32 v99, v99, v59
	v_add_f32_e32 v100, v100, v60
	v_add_f32_e32 v101, v101, v61
	v_mul_f32_e32 v98, 0xbfb8aa3b, v98
	v_mul_f32_e32 v99, 0xbfb8aa3b, v99
	v_mul_f32_e32 v100, 0xbfb8aa3b, v100
	v_mul_f32_e32 v101, 0xbfb8aa3b, v101
	v_exp_f32_e32 v98, v98
	v_exp_f32_e32 v99, v99
	v_exp_f32_e32 v100, v100
	v_exp_f32_e32 v101, v101
	v_add_f32_e32 v98, 1.0, v98
	v_add_f32_e32 v99, 1.0, v99
	v_add_f32_e32 v100, 1.0, v100
	v_add_f32_e32 v101, 1.0, v101
	v_rcp_f32_e32 v98, v98
	v_rcp_f32_e32 v99, v99
	v_rcp_f32_e32 v100, v100
	v_rcp_f32_e32 v101, v101
	v_add_f32_e32 v90, v90, v74
	v_add_f32_e32 v91, v91, v75
	v_add_f32_e32 v92, v92, v76
	v_add_f32_e32 v93, v93, v77
	v_mul_f32_e32 v90, 0xbfb8aa3b, v90
	v_mul_f32_e32 v91, 0xbfb8aa3b, v91
	v_mul_f32_e32 v92, 0xbfb8aa3b, v92
	v_mul_f32_e32 v93, 0xbfb8aa3b, v93
	s_waitcnt vmcnt(15)
	v_mov_b32_e32 v134, v168
	v_mov_b32_e32 v135, v169
	v_mov_b32_e32 v136, v170
	v_mov_b32_e32 v137, v171
	v_lshlrev_b32_e32 v129, 16, v134
	v_and_b32_e32 v130, 0xffff0000, v134
	v_lshlrev_b32_e32 v131, 16, v135
	v_and_b32_e32 v132, 0xffff0000, v135
	v_lshlrev_b32_e32 v133, 16, v136
	v_and_b32_e32 v134, 0xffff0000, v136
	v_lshlrev_b32_e32 v135, 16, v137
	v_and_b32_e32 v136, 0xffff0000, v137
	v_mul_f32_e32 v1, v1, v129
	v_mul_f32_e32 v129, v122, v133
	v_mul_f32_e32 v122, v126, v130
	v_mul_f32_e32 v126, v123, v134
	v_mul_f32_e32 v123, v127, v131
	v_mul_f32_e32 v127, v124, v135
	v_mul_f32_e32 v124, v128, v132
	v_mul_f32_e32 v125, v125, v136
	v_cvt_pk_bf16_f32 v122, v1, v122
	v_cvt_pk_bf16_f32 v123, v123, v124
	v_cvt_pk_bf16_f32 v124, v129, v126
	v_cvt_pk_bf16_f32 v125, v127, v125
	v_add_f32_e32 v1, v118, v62
	v_add_f32_e32 v118, v119, v63
	v_add_f32_e32 v119, v120, v64
	v_add_f32_e32 v120, v121, v65
	v_mul_f32_e32 v1, 0xbfb8aa3b, v1
	v_mul_f32_e32 v118, 0xbfb8aa3b, v118
	v_mul_f32_e32 v119, 0xbfb8aa3b, v119
	v_mul_f32_e32 v120, 0xbfb8aa3b, v120
	v_exp_f32_e32 v1, v1
	v_exp_f32_e32 v118, v118
	v_exp_f32_e32 v119, v119
	v_exp_f32_e32 v120, v120
	v_add_f32_e32 v1, 1.0, v1
	v_add_f32_e32 v118, 1.0, v118
	v_add_f32_e32 v119, 1.0, v119
	v_add_f32_e32 v120, 1.0, v120
	v_add_u32_e32 v130, 32, v148
	v_lshlrev_b64 v[132:133], 11, v[150:151]
	v_rcp_f32_e32 v1, v1
	v_rcp_f32_e32 v118, v118
	v_rcp_f32_e32 v119, v119
	v_rcp_f32_e32 v120, v120
	v_ashrrev_i32_e32 v131, 31, v130
	v_lshl_add_u64 v[132:133], s[60:61], 0, v[132:133]
	v_lshlrev_b64 v[134:135], 10, v[130:131]
	v_lshl_add_u64 v[132:133], v[132:133], 0, v[146:147]
	v_lshl_add_u64 v[134:135], s[80:81], 0, v[134:135]
	global_store_dwordx4 v[132:133], v[122:125], off offset:1024
	v_lshl_add_u64 v[134:135], v[134:135], 0, v[146:147]
	v_exp_f32_e32 v90, v90
	v_exp_f32_e32 v91, v91
	v_exp_f32_e32 v92, v92
	v_exp_f32_e32 v93, v93
	v_add_f32_e32 v90, 1.0, v90
	v_add_f32_e32 v91, 1.0, v91
	v_add_f32_e32 v92, 1.0, v92
	v_add_f32_e32 v93, 1.0, v93
	v_rcp_f32_e32 v90, v90
	v_rcp_f32_e32 v91, v91
	v_rcp_f32_e32 v92, v92
	v_rcp_f32_e32 v93, v93
	v_add_f32_e32 v82, v82, v58
	v_add_f32_e32 v83, v83, v59
	v_add_f32_e32 v84, v84, v60
	v_add_f32_e32 v85, v85, v61
	v_mul_f32_e32 v82, 0xbfb8aa3b, v82
	v_mul_f32_e32 v83, 0xbfb8aa3b, v83
	v_mul_f32_e32 v84, 0xbfb8aa3b, v84
	v_mul_f32_e32 v85, 0xbfb8aa3b, v85
	v_exp_f32_e32 v82, v82
	v_exp_f32_e32 v83, v83
	v_exp_f32_e32 v84, v84
	v_exp_f32_e32 v85, v85
	v_add_f32_e32 v82, 1.0, v82
	v_add_f32_e32 v83, 1.0, v83
	v_add_f32_e32 v84, 1.0, v84
	v_add_f32_e32 v85, 1.0, v85
	v_rcp_f32_e32 v82, v82
	v_rcp_f32_e32 v83, v83
	v_rcp_f32_e32 v84, v84
	v_rcp_f32_e32 v85, v85
	v_add_f32_e32 v66, v66, v74
	v_add_f32_e32 v67, v67, v75
	v_add_f32_e32 v68, v68, v76
	v_add_f32_e32 v69, v69, v77
	v_mul_f32_e32 v66, 0xbfb8aa3b, v66
	v_mul_f32_e32 v67, 0xbfb8aa3b, v67
	v_mul_f32_e32 v68, 0xbfb8aa3b, v68
	v_mul_f32_e32 v69, 0xbfb8aa3b, v69
	v_exp_f32_e32 v66, v66
	v_exp_f32_e32 v67, v67
	v_exp_f32_e32 v68, v68
	v_exp_f32_e32 v69, v69
	v_add_f32_e32 v66, 1.0, v66
	v_add_f32_e32 v67, 1.0, v67
	v_add_f32_e32 v68, 1.0, v68
	v_add_f32_e32 v69, 1.0, v69
	v_rcp_f32_e32 v66, v66
	v_rcp_f32_e32 v67, v67
	s_waitcnt vmcnt(15)
	v_mov_b32_e32 v126, v172
	v_mov_b32_e32 v127, v173
	v_mov_b32_e32 v128, v174
	v_mov_b32_e32 v129, v175
	v_lshlrev_b32_e32 v121, 16, v126
	v_and_b32_e32 v122, 0xffff0000, v126
	v_lshlrev_b32_e32 v123, 16, v127
	v_and_b32_e32 v124, 0xffff0000, v127
	v_lshlrev_b32_e32 v125, 16, v128
	v_and_b32_e32 v126, 0xffff0000, v128
	v_lshlrev_b32_e32 v127, 16, v129
	v_and_b32_e32 v128, 0xffff0000, v129
	v_mul_f32_e32 v1, v1, v121
	v_mul_f32_e32 v121, v114, v125
	v_mul_f32_e32 v114, v118, v122
	v_mul_f32_e32 v118, v115, v126
	v_mul_f32_e32 v115, v119, v123
	v_mul_f32_e32 v119, v116, v127
	v_mul_f32_e32 v116, v120, v124
	v_mul_f32_e32 v117, v117, v128
	v_cvt_pk_bf16_f32 v114, v1, v114
	v_cvt_pk_bf16_f32 v115, v115, v116
	v_cvt_pk_bf16_f32 v116, v121, v118
	v_cvt_pk_bf16_f32 v117, v119, v117
	v_add_f32_e32 v1, v110, v78
	v_add_f32_e32 v110, v111, v79
	v_add_f32_e32 v111, v112, v80
	v_add_f32_e32 v112, v113, v81
	v_mul_f32_e32 v1, 0xbfb8aa3b, v1
	v_mul_f32_e32 v110, 0xbfb8aa3b, v110
	v_mul_f32_e32 v111, 0xbfb8aa3b, v111
	v_mul_f32_e32 v112, 0xbfb8aa3b, v112
	v_exp_f32_e32 v1, v1
	v_exp_f32_e32 v110, v110
	v_exp_f32_e32 v111, v111
	v_exp_f32_e32 v112, v112
	v_add_f32_e32 v1, 1.0, v1
	v_add_f32_e32 v110, 1.0, v110
	v_add_f32_e32 v111, 1.0, v111
	v_add_f32_e32 v112, 1.0, v112
	v_rcp_f32_e32 v1, v1
	v_rcp_f32_e32 v110, v110
	v_rcp_f32_e32 v111, v111
	v_rcp_f32_e32 v112, v112
	global_store_dwordx4 v[132:133], v[114:117], off offset:1280
	v_rcp_f32_e32 v68, v68
	v_rcp_f32_e32 v69, v69
	v_add_f32_e32 v50, v50, v58
	v_add_f32_e32 v51, v51, v59
	v_add_f32_e32 v52, v52, v60
	v_add_f32_e32 v53, v53, v61
	v_mul_f32_e32 v50, 0xbfb8aa3b, v50
	v_mul_f32_e32 v51, 0xbfb8aa3b, v51
	v_mul_f32_e32 v52, 0xbfb8aa3b, v52
	v_mul_f32_e32 v53, 0xbfb8aa3b, v53
	v_exp_f32_e32 v50, v50
	v_exp_f32_e32 v51, v51
	v_exp_f32_e32 v52, v52
	v_exp_f32_e32 v53, v53
	v_add_f32_e32 v50, 1.0, v50
	v_add_f32_e32 v51, 1.0, v51
	v_add_f32_e32 v52, 1.0, v52
	v_add_f32_e32 v53, 1.0, v53
	v_rcp_f32_e32 v50, v50
	v_rcp_f32_e32 v51, v51
	v_rcp_f32_e32 v52, v52
	v_rcp_f32_e32 v53, v53
	v_add_f32_e32 v42, v42, v74
	v_add_f32_e32 v43, v43, v75
	v_add_f32_e32 v44, v44, v76
	v_add_f32_e32 v45, v45, v77
	v_mul_f32_e32 v42, 0xbfb8aa3b, v42
	v_mul_f32_e32 v43, 0xbfb8aa3b, v43
	v_mul_f32_e32 v44, 0xbfb8aa3b, v44
	v_mul_f32_e32 v45, 0xbfb8aa3b, v45
	v_exp_f32_e32 v42, v42
	v_exp_f32_e32 v43, v43
	v_exp_f32_e32 v44, v44
	v_exp_f32_e32 v45, v45
	v_add_f32_e32 v42, 1.0, v42
	v_add_f32_e32 v43, 1.0, v43
	v_add_f32_e32 v44, 1.0, v44
	v_add_f32_e32 v45, 1.0, v45
	v_rcp_f32_e32 v42, v42
	v_rcp_f32_e32 v43, v43
	v_rcp_f32_e32 v44, v44
	v_rcp_f32_e32 v45, v45
	v_add_f32_e32 v34, v34, v58
	v_add_f32_e32 v35, v35, v59
	v_add_f32_e32 v36, v36, v60
	v_add_f32_e32 v37, v37, v61
	v_mul_f32_e32 v34, 0xbfb8aa3b, v34
	v_mul_f32_e32 v35, 0xbfb8aa3b, v35
	v_mul_f32_e32 v36, 0xbfb8aa3b, v36
	v_mul_f32_e32 v37, 0xbfb8aa3b, v37
	v_exp_f32_e32 v34, v34
	v_exp_f32_e32 v35, v35
	v_exp_f32_e32 v36, v36
	v_exp_f32_e32 v37, v37
	v_add_f32_e32 v34, 1.0, v34
	v_add_f32_e32 v35, 1.0, v35
	v_add_f32_e32 v36, 1.0, v36
	v_add_f32_e32 v37, 1.0, v37
	s_waitcnt vmcnt(15)
	v_mov_b32_e32 v118, v176
	v_mov_b32_e32 v119, v177
	v_mov_b32_e32 v120, v178
	v_mov_b32_e32 v121, v179
	v_lshlrev_b32_e32 v113, 16, v118
	v_and_b32_e32 v114, 0xffff0000, v118
	v_lshlrev_b32_e32 v115, 16, v119
	v_and_b32_e32 v116, 0xffff0000, v119
	v_lshlrev_b32_e32 v117, 16, v120
	v_and_b32_e32 v118, 0xffff0000, v120
	v_lshlrev_b32_e32 v119, 16, v121
	v_and_b32_e32 v120, 0xffff0000, v121
	v_mul_f32_e32 v1, v1, v113
	v_mul_f32_e32 v113, v106, v117
	v_mul_f32_e32 v106, v110, v114
	v_mul_f32_e32 v110, v107, v118
	v_mul_f32_e32 v107, v111, v115
	v_mul_f32_e32 v111, v108, v119
	v_mul_f32_e32 v108, v112, v116
	v_mul_f32_e32 v109, v109, v120
	v_cvt_pk_bf16_f32 v106, v1, v106
	v_cvt_pk_bf16_f32 v107, v107, v108
	v_cvt_pk_bf16_f32 v108, v113, v110
	v_cvt_pk_bf16_f32 v109, v111, v109
	v_add_f32_e32 v1, v102, v62
	v_add_f32_e32 v102, v103, v63
	v_add_f32_e32 v103, v104, v64
	v_add_f32_e32 v104, v105, v65
	v_mul_f32_e32 v1, 0xbfb8aa3b, v1
	v_mul_f32_e32 v102, 0xbfb8aa3b, v102
	v_mul_f32_e32 v103, 0xbfb8aa3b, v103
	v_mul_f32_e32 v104, 0xbfb8aa3b, v104
	v_exp_f32_e32 v1, v1
	v_exp_f32_e32 v102, v102
	v_exp_f32_e32 v103, v103
	v_exp_f32_e32 v104, v104
	v_add_f32_e32 v1, 1.0, v1
	v_add_f32_e32 v102, 1.0, v102
	v_add_f32_e32 v103, 1.0, v103
	v_add_f32_e32 v104, 1.0, v104
	v_add_u32_e32 v114, 0xffff15a0, v148
	v_lshlrev_b64 v[116:117], 11, v[130:131]
	v_rcp_f32_e32 v1, v1
	v_rcp_f32_e32 v102, v102
	v_rcp_f32_e32 v103, v103
	v_rcp_f32_e32 v104, v104
	v_ashrrev_i32_e32 v115, 31, v114
	v_lshl_add_u64 v[116:117], s[60:61], 0, v[116:117]
	v_lshlrev_b64 v[118:119], 10, v[114:115]
	v_lshl_add_u64 v[116:117], v[116:117], 0, v[146:147]
	v_lshl_add_u64 v[118:119], s[80:81], 0, v[118:119]
	global_store_dwordx4 v[116:117], v[106:109], off offset:1024
	v_lshl_add_u64 v[118:119], v[118:119], 0, v[146:147]
	v_rcp_f32_e32 v34, v34
	v_rcp_f32_e32 v35, v35
	v_rcp_f32_e32 v36, v36
	v_rcp_f32_e32 v37, v37
	v_add_f32_e32 v26, v26, v74
	v_add_f32_e32 v27, v27, v75
	v_add_f32_e32 v28, v28, v76
	v_add_f32_e32 v29, v29, v77
	v_mul_f32_e32 v26, 0xbfb8aa3b, v26
	v_mul_f32_e32 v27, 0xbfb8aa3b, v27
	v_mul_f32_e32 v28, 0xbfb8aa3b, v28
	v_mul_f32_e32 v29, 0xbfb8aa3b, v29
	v_exp_f32_e32 v26, v26
	v_exp_f32_e32 v27, v27
	v_exp_f32_e32 v28, v28
	v_exp_f32_e32 v29, v29
	v_add_f32_e32 v26, 1.0, v26
	v_add_f32_e32 v27, 1.0, v27
	v_add_f32_e32 v28, 1.0, v28
	v_add_f32_e32 v29, 1.0, v29
	v_rcp_f32_e32 v26, v26
	v_rcp_f32_e32 v27, v27
	v_rcp_f32_e32 v28, v28
	v_rcp_f32_e32 v29, v29
	v_add_f32_e32 v18, v18, v58
	v_add_f32_e32 v19, v19, v59
	v_add_f32_e32 v20, v20, v60
	v_add_f32_e32 v21, v21, v61
	v_mul_f32_e32 v18, 0xbfb8aa3b, v18
	v_mul_f32_e32 v19, 0xbfb8aa3b, v19
	v_mul_f32_e32 v20, 0xbfb8aa3b, v20
	v_mul_f32_e32 v21, 0xbfb8aa3b, v21
	v_exp_f32_e32 v18, v18
	v_exp_f32_e32 v19, v19
	v_exp_f32_e32 v20, v20
	v_exp_f32_e32 v21, v21
	v_add_f32_e32 v18, 1.0, v18
	v_add_f32_e32 v19, 1.0, v19
	v_add_f32_e32 v20, 1.0, v20
	v_add_f32_e32 v21, 1.0, v21
	v_rcp_f32_e32 v18, v18
	v_rcp_f32_e32 v19, v19
	v_rcp_f32_e32 v20, v20
	v_rcp_f32_e32 v21, v21
	v_add_f32_e32 v10, v10, v74
	v_add_f32_e32 v11, v11, v75
	v_add_f32_e32 v12, v12, v76
	v_add_f32_e32 v13, v13, v77
	v_mul_f32_e32 v10, 0xbfb8aa3b, v10
	v_mul_f32_e32 v11, 0xbfb8aa3b, v11
	s_waitcnt vmcnt(15)
	v_mov_b32_e32 v110, v180
	v_mov_b32_e32 v111, v181
	v_mov_b32_e32 v112, v182
	v_mov_b32_e32 v113, v183
	v_lshlrev_b32_e32 v105, 16, v110
	v_and_b32_e32 v106, 0xffff0000, v110
	v_lshlrev_b32_e32 v107, 16, v111
	v_and_b32_e32 v108, 0xffff0000, v111
	v_lshlrev_b32_e32 v109, 16, v112
	v_and_b32_e32 v110, 0xffff0000, v112
	v_lshlrev_b32_e32 v111, 16, v113
	v_and_b32_e32 v112, 0xffff0000, v113
	v_mul_f32_e32 v1, v1, v105
	v_mul_f32_e32 v105, v98, v109
	v_mul_f32_e32 v98, v102, v106
	v_mul_f32_e32 v102, v99, v110
	v_mul_f32_e32 v99, v103, v107
	v_mul_f32_e32 v103, v100, v111
	v_mul_f32_e32 v100, v104, v108
	v_mul_f32_e32 v101, v101, v112
	v_cvt_pk_bf16_f32 v98, v1, v98
	v_cvt_pk_bf16_f32 v99, v99, v100
	v_cvt_pk_bf16_f32 v100, v105, v102
	v_cvt_pk_bf16_f32 v101, v103, v101
	v_add_f32_e32 v1, v94, v78
	v_add_f32_e32 v94, v95, v79
	v_add_f32_e32 v95, v96, v80
	v_add_f32_e32 v96, v97, v81
	v_mul_f32_e32 v1, 0xbfb8aa3b, v1
	v_mul_f32_e32 v94, 0xbfb8aa3b, v94
	v_mul_f32_e32 v95, 0xbfb8aa3b, v95
	v_mul_f32_e32 v96, 0xbfb8aa3b, v96
	v_exp_f32_e32 v1, v1
	v_exp_f32_e32 v94, v94
	v_exp_f32_e32 v95, v95
	v_exp_f32_e32 v96, v96
	v_add_f32_e32 v1, 1.0, v1
	v_add_f32_e32 v94, 1.0, v94
	v_add_f32_e32 v95, 1.0, v95
	v_add_f32_e32 v96, 1.0, v96
	v_rcp_f32_e32 v1, v1
	v_rcp_f32_e32 v94, v94
	v_rcp_f32_e32 v95, v95
	v_rcp_f32_e32 v96, v96
	global_store_dwordx4 v[116:117], v[98:101], off offset:1280
	v_mul_f32_e32 v12, 0xbfb8aa3b, v12
	v_mul_f32_e32 v13, 0xbfb8aa3b, v13
	v_exp_f32_e32 v10, v10
	v_exp_f32_e32 v11, v11
	v_exp_f32_e32 v12, v12
	v_exp_f32_e32 v13, v13
	v_add_f32_e32 v10, 1.0, v10
	v_add_f32_e32 v11, 1.0, v11
	v_add_f32_e32 v12, 1.0, v12
	v_add_f32_e32 v13, 1.0, v13
	v_rcp_f32_e32 v10, v10
	v_rcp_f32_e32 v11, v11
	v_rcp_f32_e32 v12, v12
	v_rcp_f32_e32 v13, v13
	v_add_f32_e32 v2, v2, v58
	v_add_f32_e32 v3, v3, v59
	v_add_f32_e32 v4, v4, v60
	v_add_f32_e32 v5, v5, v61
	v_mul_f32_e32 v2, 0xbfb8aa3b, v2
	v_mul_f32_e32 v3, 0xbfb8aa3b, v3
	v_mul_f32_e32 v4, 0xbfb8aa3b, v4
	v_mul_f32_e32 v5, 0xbfb8aa3b, v5
	v_exp_f32_e32 v2, v2
	v_exp_f32_e32 v3, v3
	v_exp_f32_e32 v4, v4
	v_exp_f32_e32 v5, v5
	v_add_f32_e32 v2, 1.0, v2
	v_add_f32_e32 v3, 1.0, v3
	v_add_f32_e32 v4, 1.0, v4
	v_add_f32_e32 v5, 1.0, v5
	v_rcp_f32_e32 v2, v2
	v_rcp_f32_e32 v3, v3
	v_rcp_f32_e32 v4, v4
	v_rcp_f32_e32 v5, v5
	s_waitcnt vmcnt(15)
	v_mov_b32_e32 v102, v184
	v_mov_b32_e32 v103, v185
	v_mov_b32_e32 v104, v186
	v_mov_b32_e32 v105, v187
	v_lshlrev_b32_e32 v97, 16, v102
	v_and_b32_e32 v98, 0xffff0000, v102
	v_lshlrev_b32_e32 v99, 16, v103
	v_and_b32_e32 v100, 0xffff0000, v103
	v_lshlrev_b32_e32 v101, 16, v104
	v_and_b32_e32 v102, 0xffff0000, v104
	v_lshlrev_b32_e32 v103, 16, v105
	v_and_b32_e32 v104, 0xffff0000, v105
	v_mul_f32_e32 v1, v1, v97
	v_mul_f32_e32 v97, v90, v101
	v_mul_f32_e32 v90, v94, v98
	v_mul_f32_e32 v94, v91, v102
	v_mul_f32_e32 v91, v95, v99
	v_mul_f32_e32 v95, v92, v103
	v_mul_f32_e32 v92, v96, v100
	v_mul_f32_e32 v93, v93, v104
	v_cvt_pk_bf16_f32 v90, v1, v90
	v_cvt_pk_bf16_f32 v91, v91, v92
	v_cvt_pk_bf16_f32 v92, v97, v94
	v_cvt_pk_bf16_f32 v93, v95, v93
	v_add_f32_e32 v1, v86, v62
	v_add_f32_e32 v86, v87, v63
	v_add_f32_e32 v87, v88, v64
	v_add_f32_e32 v88, v89, v65
	v_mul_f32_e32 v1, 0xbfb8aa3b, v1
	v_mul_f32_e32 v86, 0xbfb8aa3b, v86
	v_mul_f32_e32 v87, 0xbfb8aa3b, v87
	v_mul_f32_e32 v88, 0xbfb8aa3b, v88
	v_exp_f32_e32 v1, v1
	v_exp_f32_e32 v86, v86
	v_exp_f32_e32 v87, v87
	v_exp_f32_e32 v88, v88
	v_add_f32_e32 v1, 1.0, v1
	v_add_f32_e32 v86, 1.0, v86
	v_add_f32_e32 v87, 1.0, v87
	v_add_f32_e32 v88, 1.0, v88
	v_add_u32_e32 v98, 0x60, v148
	v_lshlrev_b64 v[100:101], 11, v[114:115]
	v_rcp_f32_e32 v1, v1
	v_rcp_f32_e32 v86, v86
	v_rcp_f32_e32 v87, v87
	v_rcp_f32_e32 v88, v88
	v_ashrrev_i32_e32 v99, 31, v98
	v_lshl_add_u64 v[100:101], s[60:61], 0, v[100:101]
	v_lshlrev_b64 v[102:103], 10, v[98:99]
	v_lshl_add_u64 v[100:101], v[100:101], 0, v[146:147]
	v_lshl_add_u64 v[102:103], s[80:81], 0, v[102:103]
	global_store_dwordx4 v[100:101], v[90:93], off offset:1024
	v_lshl_add_u64 v[102:103], v[102:103], 0, v[146:147]
	s_waitcnt vmcnt(15)
	v_mov_b32_e32 v94, v188
	v_mov_b32_e32 v95, v189
	v_mov_b32_e32 v96, v190
	v_mov_b32_e32 v97, v191
	v_lshlrev_b32_e32 v89, 16, v94
	v_and_b32_e32 v90, 0xffff0000, v94
	v_lshlrev_b32_e32 v91, 16, v95
	v_and_b32_e32 v92, 0xffff0000, v95
	v_lshlrev_b32_e32 v93, 16, v96
	v_and_b32_e32 v94, 0xffff0000, v96
	v_lshlrev_b32_e32 v95, 16, v97
	v_and_b32_e32 v96, 0xffff0000, v97
	v_mul_f32_e32 v1, v1, v89
	v_mul_f32_e32 v89, v82, v93
	v_mul_f32_e32 v82, v86, v90
	v_mul_f32_e32 v86, v83, v94
	v_mul_f32_e32 v83, v87, v91
	v_mul_f32_e32 v87, v84, v95
	v_mul_f32_e32 v84, v88, v92
	v_mul_f32_e32 v85, v85, v96
	v_cvt_pk_bf16_f32 v82, v1, v82
	v_cvt_pk_bf16_f32 v83, v83, v84
	v_cvt_pk_bf16_f32 v84, v89, v86
	v_cvt_pk_bf16_f32 v85, v87, v85
	v_add_f32_e32 v1, v70, v78
	v_add_f32_e32 v70, v71, v79
	v_add_f32_e32 v71, v72, v80
	v_add_f32_e32 v72, v73, v81
	v_mul_f32_e32 v1, 0xbfb8aa3b, v1
	v_mul_f32_e32 v70, 0xbfb8aa3b, v70
	v_mul_f32_e32 v71, 0xbfb8aa3b, v71
	v_mul_f32_e32 v72, 0xbfb8aa3b, v72
	v_exp_f32_e32 v1, v1
	v_exp_f32_e32 v70, v70
	v_exp_f32_e32 v71, v71
	v_exp_f32_e32 v72, v72
	v_add_f32_e32 v1, 1.0, v1
	v_add_f32_e32 v70, 1.0, v70
	v_add_f32_e32 v71, 1.0, v71
	v_add_f32_e32 v72, 1.0, v72
	v_rcp_f32_e32 v1, v1
	v_rcp_f32_e32 v70, v70
	v_rcp_f32_e32 v71, v71
	v_rcp_f32_e32 v72, v72
	global_store_dwordx4 v[100:101], v[82:85], off offset:1280
	s_waitcnt vmcnt(15)
	v_mov_b32_e32 v86, v192
	v_mov_b32_e32 v87, v193
	v_mov_b32_e32 v88, v194
	v_mov_b32_e32 v89, v195
	v_lshlrev_b32_e32 v73, 16, v86
	v_and_b32_e32 v82, 0xffff0000, v86
	v_lshlrev_b32_e32 v83, 16, v87
	v_and_b32_e32 v84, 0xffff0000, v87
	v_lshlrev_b32_e32 v85, 16, v88
	v_and_b32_e32 v86, 0xffff0000, v88
	v_lshlrev_b32_e32 v87, 16, v89
	v_and_b32_e32 v88, 0xffff0000, v89
	v_mul_f32_e32 v1, v1, v73
	v_mul_f32_e32 v73, v66, v85
	v_mul_f32_e32 v66, v70, v82
	v_mul_f32_e32 v70, v67, v86
	v_mul_f32_e32 v67, v71, v83
	v_mul_f32_e32 v71, v68, v87
	v_mul_f32_e32 v68, v72, v84
	v_mul_f32_e32 v69, v69, v88
	v_cvt_pk_bf16_f32 v66, v1, v66
	v_cvt_pk_bf16_f32 v67, v67, v68
	v_cvt_pk_bf16_f32 v68, v73, v70
	v_cvt_pk_bf16_f32 v69, v71, v69
	v_add_f32_e32 v1, v54, v62
	v_add_f32_e32 v54, v55, v63
	v_add_f32_e32 v55, v56, v64
	v_add_f32_e32 v56, v57, v65
	v_mul_f32_e32 v1, 0xbfb8aa3b, v1
	v_mul_f32_e32 v54, 0xbfb8aa3b, v54
	v_mul_f32_e32 v55, 0xbfb8aa3b, v55
	v_mul_f32_e32 v56, 0xbfb8aa3b, v56
	v_exp_f32_e32 v1, v1
	v_exp_f32_e32 v54, v54
	v_exp_f32_e32 v55, v55
	v_exp_f32_e32 v56, v56
	v_add_f32_e32 v1, 1.0, v1
	v_add_f32_e32 v54, 1.0, v54
	v_add_f32_e32 v55, 1.0, v55
	v_add_f32_e32 v56, 1.0, v56
	v_add_u32_e32 v82, 0x70, v148
	v_lshlrev_b64 v[84:85], 11, v[98:99]
	v_rcp_f32_e32 v1, v1
	v_rcp_f32_e32 v54, v54
	v_rcp_f32_e32 v55, v55
	v_rcp_f32_e32 v56, v56
	v_ashrrev_i32_e32 v83, 31, v82
	v_lshl_add_u64 v[84:85], s[60:61], 0, v[84:85]
	v_lshlrev_b64 v[86:87], 10, v[82:83]
	v_lshl_add_u64 v[84:85], v[84:85], 0, v[146:147]
	v_lshl_add_u64 v[86:87], s[80:81], 0, v[86:87]
	global_store_dwordx4 v[84:85], v[66:69], off offset:1024
	v_lshl_add_u64 v[86:87], v[86:87], 0, v[146:147]
	s_waitcnt vmcnt(15)
	v_mov_b32_e32 v70, v196
	v_mov_b32_e32 v71, v197
	v_mov_b32_e32 v72, v198
	v_mov_b32_e32 v73, v199
	v_lshlrev_b32_e32 v57, 16, v70
	v_and_b32_e32 v66, 0xffff0000, v70
	v_lshlrev_b32_e32 v67, 16, v71
	v_and_b32_e32 v68, 0xffff0000, v71
	v_lshlrev_b32_e32 v69, 16, v72
	v_and_b32_e32 v70, 0xffff0000, v72
	v_lshlrev_b32_e32 v71, 16, v73
	v_and_b32_e32 v72, 0xffff0000, v73
	v_mul_f32_e32 v1, v1, v57
	v_mul_f32_e32 v57, v50, v69
	v_mul_f32_e32 v50, v54, v66
	v_mul_f32_e32 v54, v51, v70
	v_mul_f32_e32 v51, v55, v67
	v_mul_f32_e32 v55, v52, v71
	v_mul_f32_e32 v52, v56, v68
	v_mul_f32_e32 v53, v53, v72
	v_cvt_pk_bf16_f32 v50, v1, v50
	v_cvt_pk_bf16_f32 v51, v51, v52
	v_cvt_pk_bf16_f32 v52, v57, v54
	v_cvt_pk_bf16_f32 v53, v55, v53
	v_add_f32_e32 v1, v46, v78
	v_add_f32_e32 v46, v47, v79
	v_add_f32_e32 v47, v48, v80
	v_add_f32_e32 v48, v49, v81
	v_mul_f32_e32 v1, 0xbfb8aa3b, v1
	v_mul_f32_e32 v46, 0xbfb8aa3b, v46
	v_mul_f32_e32 v47, 0xbfb8aa3b, v47
	v_mul_f32_e32 v48, 0xbfb8aa3b, v48
	v_exp_f32_e32 v1, v1
	v_exp_f32_e32 v46, v46
	v_exp_f32_e32 v47, v47
	v_exp_f32_e32 v48, v48
	v_add_f32_e32 v1, 1.0, v1
	v_add_f32_e32 v46, 1.0, v46
	v_add_f32_e32 v47, 1.0, v47
	v_add_f32_e32 v48, 1.0, v48
	v_rcp_f32_e32 v1, v1
	v_rcp_f32_e32 v46, v46
	v_rcp_f32_e32 v47, v47
	v_rcp_f32_e32 v48, v48
	global_store_dwordx4 v[84:85], v[50:53], off offset:1280
	s_waitcnt vmcnt(15)
	v_mov_b32_e32 v54, v200
	v_mov_b32_e32 v55, v201
	v_mov_b32_e32 v56, v202
	v_mov_b32_e32 v57, v203
	v_lshlrev_b32_e32 v49, 16, v54
	v_and_b32_e32 v50, 0xffff0000, v54
	v_lshlrev_b32_e32 v51, 16, v55
	v_and_b32_e32 v52, 0xffff0000, v55
	v_lshlrev_b32_e32 v53, 16, v56
	v_and_b32_e32 v54, 0xffff0000, v56
	v_lshlrev_b32_e32 v55, 16, v57
	v_and_b32_e32 v56, 0xffff0000, v57
	v_mul_f32_e32 v1, v1, v49
	v_mul_f32_e32 v49, v42, v53
	v_mul_f32_e32 v42, v46, v50
	v_mul_f32_e32 v46, v43, v54
	v_mul_f32_e32 v43, v47, v51
	v_mul_f32_e32 v47, v44, v55
	v_mul_f32_e32 v44, v48, v52
	v_mul_f32_e32 v45, v45, v56
	v_cvt_pk_bf16_f32 v42, v1, v42
	v_cvt_pk_bf16_f32 v43, v43, v44
	v_cvt_pk_bf16_f32 v44, v49, v46
	v_cvt_pk_bf16_f32 v45, v47, v45
	v_add_f32_e32 v1, v38, v62
	v_add_f32_e32 v38, v39, v63
	v_add_f32_e32 v39, v40, v64
	v_add_f32_e32 v40, v41, v65
	v_mul_f32_e32 v1, 0xbfb8aa3b, v1
	v_mul_f32_e32 v38, 0xbfb8aa3b, v38
	v_mul_f32_e32 v39, 0xbfb8aa3b, v39
	v_mul_f32_e32 v40, 0xbfb8aa3b, v40
	v_exp_f32_e32 v1, v1
	v_exp_f32_e32 v38, v38
	v_exp_f32_e32 v39, v39
	v_exp_f32_e32 v40, v40
	v_add_f32_e32 v1, 1.0, v1
	v_add_f32_e32 v38, 1.0, v38
	v_add_f32_e32 v39, 1.0, v39
	v_add_f32_e32 v40, 1.0, v40
	v_add_u32_e32 v50, 0x80, v148
	v_lshlrev_b64 v[52:53], 11, v[82:83]
	v_rcp_f32_e32 v1, v1
	v_rcp_f32_e32 v38, v38
	v_rcp_f32_e32 v39, v39
	v_rcp_f32_e32 v40, v40
	v_ashrrev_i32_e32 v51, 31, v50
	v_lshl_add_u64 v[52:53], s[60:61], 0, v[52:53]
	v_lshlrev_b64 v[54:55], 10, v[50:51]
	v_lshl_add_u64 v[52:53], v[52:53], 0, v[146:147]
	v_lshl_add_u64 v[54:55], s[80:81], 0, v[54:55]
	global_store_dwordx4 v[52:53], v[42:45], off offset:1024
	v_lshl_add_u64 v[54:55], v[54:55], 0, v[146:147]
	s_waitcnt vmcnt(15)
	v_mov_b32_e32 v46, v204
	v_mov_b32_e32 v47, v205
	v_mov_b32_e32 v48, v206
	v_mov_b32_e32 v49, v207
	v_lshlrev_b32_e32 v41, 16, v46
	v_and_b32_e32 v42, 0xffff0000, v46
	v_lshlrev_b32_e32 v43, 16, v47
	v_and_b32_e32 v44, 0xffff0000, v47
	v_lshlrev_b32_e32 v45, 16, v48
	v_and_b32_e32 v46, 0xffff0000, v48
	v_lshlrev_b32_e32 v47, 16, v49
	v_and_b32_e32 v48, 0xffff0000, v49
	v_mul_f32_e32 v1, v1, v41
	v_mul_f32_e32 v41, v34, v45
	v_mul_f32_e32 v34, v38, v42
	v_mul_f32_e32 v38, v35, v46
	v_mul_f32_e32 v35, v39, v43
	v_mul_f32_e32 v39, v36, v47
	v_mul_f32_e32 v36, v40, v44
	v_mul_f32_e32 v37, v37, v48
	v_cvt_pk_bf16_f32 v34, v1, v34
	v_cvt_pk_bf16_f32 v35, v35, v36
	v_cvt_pk_bf16_f32 v36, v41, v38
	v_cvt_pk_bf16_f32 v37, v39, v37
	v_add_f32_e32 v1, v30, v78
	v_add_f32_e32 v30, v31, v79
	v_add_f32_e32 v31, v32, v80
	v_add_f32_e32 v32, v33, v81
	v_mul_f32_e32 v1, 0xbfb8aa3b, v1
	v_mul_f32_e32 v30, 0xbfb8aa3b, v30
	v_mul_f32_e32 v31, 0xbfb8aa3b, v31
	v_mul_f32_e32 v32, 0xbfb8aa3b, v32
	v_exp_f32_e32 v1, v1
	v_exp_f32_e32 v30, v30
	v_exp_f32_e32 v31, v31
	v_exp_f32_e32 v32, v32
	v_add_f32_e32 v1, 1.0, v1
	v_add_f32_e32 v30, 1.0, v30
	v_add_f32_e32 v31, 1.0, v31
	v_add_f32_e32 v32, 1.0, v32
	v_rcp_f32_e32 v1, v1
	v_rcp_f32_e32 v30, v30
	v_rcp_f32_e32 v31, v31
	v_rcp_f32_e32 v32, v32
	global_store_dwordx4 v[52:53], v[34:37], off offset:1280
	s_waitcnt vmcnt(15)
	v_mov_b32_e32 v38, v208
	v_mov_b32_e32 v39, v209
	v_mov_b32_e32 v40, v210
	v_mov_b32_e32 v41, v211
	v_lshlrev_b32_e32 v33, 16, v38
	v_and_b32_e32 v34, 0xffff0000, v38
	v_lshlrev_b32_e32 v35, 16, v39
	v_and_b32_e32 v36, 0xffff0000, v39
	v_lshlrev_b32_e32 v37, 16, v40
	v_and_b32_e32 v38, 0xffff0000, v40
	v_lshlrev_b32_e32 v39, 16, v41
	v_and_b32_e32 v40, 0xffff0000, v41
	v_mul_f32_e32 v1, v1, v33
	v_mul_f32_e32 v33, v26, v37
	v_mul_f32_e32 v26, v30, v34
	v_mul_f32_e32 v30, v27, v38
	v_mul_f32_e32 v27, v31, v35
	v_mul_f32_e32 v31, v28, v39
	v_mul_f32_e32 v28, v32, v36
	v_mul_f32_e32 v29, v29, v40
	v_cvt_pk_bf16_f32 v26, v1, v26
	v_cvt_pk_bf16_f32 v27, v27, v28
	v_cvt_pk_bf16_f32 v28, v33, v30
	v_cvt_pk_bf16_f32 v29, v31, v29
	v_add_f32_e32 v1, v22, v62
	v_add_f32_e32 v22, v23, v63
	v_add_f32_e32 v23, v24, v64
	v_add_f32_e32 v24, v25, v65
	v_mul_f32_e32 v1, 0xbfb8aa3b, v1
	v_mul_f32_e32 v22, 0xbfb8aa3b, v22
	v_mul_f32_e32 v23, 0xbfb8aa3b, v23
	v_mul_f32_e32 v24, 0xbfb8aa3b, v24
	v_exp_f32_e32 v1, v1
	v_exp_f32_e32 v22, v22
	v_exp_f32_e32 v23, v23
	v_exp_f32_e32 v24, v24
	v_add_f32_e32 v1, 1.0, v1
	v_add_f32_e32 v22, 1.0, v22
	v_add_f32_e32 v23, 1.0, v23
	v_add_f32_e32 v24, 1.0, v24
	v_add_u32_e32 v34, 0xffff15a0, v148
	v_lshlrev_b64 v[36:37], 11, v[50:51]
	v_rcp_f32_e32 v1, v1
	v_rcp_f32_e32 v22, v22
	v_rcp_f32_e32 v23, v23
	v_rcp_f32_e32 v24, v24
	v_ashrrev_i32_e32 v35, 31, v34
	v_lshl_add_u64 v[36:37], s[60:61], 0, v[36:37]
	v_lshlrev_b64 v[38:39], 10, v[34:35]
	v_lshl_add_u64 v[36:37], v[36:37], 0, v[146:147]
	v_lshl_add_u64 v[38:39], s[80:81], 0, v[38:39]
	global_store_dwordx4 v[36:37], v[26:29], off offset:1024
	v_lshl_add_u64 v[38:39], v[38:39], 0, v[146:147]
	s_waitcnt vmcnt(15)
	v_mov_b32_e32 v30, v216
	v_mov_b32_e32 v31, v217
	v_mov_b32_e32 v32, v218
	v_mov_b32_e32 v33, v219
	v_lshlrev_b32_e32 v25, 16, v30
	v_and_b32_e32 v26, 0xffff0000, v30
	v_lshlrev_b32_e32 v27, 16, v31
	v_and_b32_e32 v28, 0xffff0000, v31
	v_lshlrev_b32_e32 v29, 16, v32
	v_and_b32_e32 v30, 0xffff0000, v32
	v_lshlrev_b32_e32 v31, 16, v33
	v_and_b32_e32 v32, 0xffff0000, v33
	v_mul_f32_e32 v1, v1, v25
	v_mul_f32_e32 v25, v18, v29
	v_mul_f32_e32 v18, v22, v26
	v_mul_f32_e32 v22, v19, v30
	v_mul_f32_e32 v19, v23, v27
	v_mul_f32_e32 v23, v20, v31
	v_mul_f32_e32 v20, v24, v28
	v_mul_f32_e32 v21, v21, v32
	v_cvt_pk_bf16_f32 v18, v1, v18
	v_cvt_pk_bf16_f32 v19, v19, v20
	v_cvt_pk_bf16_f32 v20, v25, v22
	v_cvt_pk_bf16_f32 v21, v23, v21
	v_add_f32_e32 v1, v14, v78
	v_add_f32_e32 v14, v15, v79
	v_add_f32_e32 v15, v16, v80
	v_add_f32_e32 v16, v17, v81
	v_mul_f32_e32 v1, 0xbfb8aa3b, v1
	v_mul_f32_e32 v14, 0xbfb8aa3b, v14
	v_mul_f32_e32 v15, 0xbfb8aa3b, v15
	v_mul_f32_e32 v16, 0xbfb8aa3b, v16
	v_exp_f32_e32 v1, v1
	v_exp_f32_e32 v14, v14
	v_exp_f32_e32 v15, v15
	v_exp_f32_e32 v16, v16
	v_add_f32_e32 v1, 1.0, v1
	v_add_f32_e32 v14, 1.0, v14
	v_add_f32_e32 v15, 1.0, v15
	v_add_f32_e32 v16, 1.0, v16
	v_rcp_f32_e32 v1, v1
	v_rcp_f32_e32 v14, v14
	v_rcp_f32_e32 v15, v15
	v_rcp_f32_e32 v16, v16
	global_store_dwordx4 v[36:37], v[18:21], off offset:1280
	s_waitcnt vmcnt(15)
	v_mov_b32_e32 v22, v220
	v_mov_b32_e32 v23, v221
	v_mov_b32_e32 v24, v222
	v_mov_b32_e32 v25, v223
	v_lshlrev_b32_e32 v17, 16, v22
	v_and_b32_e32 v18, 0xffff0000, v22
	v_lshlrev_b32_e32 v19, 16, v23
	v_and_b32_e32 v20, 0xffff0000, v23
	v_lshlrev_b32_e32 v21, 16, v24
	v_and_b32_e32 v22, 0xffff0000, v24
	v_lshlrev_b32_e32 v23, 16, v25
	v_and_b32_e32 v24, 0xffff0000, v25
	v_mul_f32_e32 v1, v1, v17
	v_mul_f32_e32 v17, v10, v21
	v_mul_f32_e32 v10, v14, v18
	v_mul_f32_e32 v14, v11, v22
	v_mul_f32_e32 v11, v15, v19
	v_mul_f32_e32 v15, v12, v23
	v_mul_f32_e32 v12, v16, v20
	v_mul_f32_e32 v13, v13, v24
	v_cvt_pk_bf16_f32 v10, v1, v10
	v_cvt_pk_bf16_f32 v11, v11, v12
	v_cvt_pk_bf16_f32 v12, v17, v14
	v_cvt_pk_bf16_f32 v13, v15, v13
	v_add_f32_e32 v1, v6, v62
	v_add_f32_e32 v6, v7, v63
	v_add_f32_e32 v7, v8, v64
	v_add_f32_e32 v8, v9, v65
	v_mul_f32_e32 v1, 0xbfb8aa3b, v1
	v_mul_f32_e32 v6, 0xbfb8aa3b, v6
	v_mul_f32_e32 v7, 0xbfb8aa3b, v7
	v_mul_f32_e32 v8, 0xbfb8aa3b, v8
	v_exp_f32_e32 v1, v1
	v_exp_f32_e32 v6, v6
	v_exp_f32_e32 v7, v7
	v_exp_f32_e32 v8, v8
	v_add_f32_e32 v1, 1.0, v1
	v_add_f32_e32 v6, 1.0, v6
	v_add_f32_e32 v7, 1.0, v7
	v_add_f32_e32 v8, 1.0, v8
	v_lshlrev_b64 v[18:19], 11, v[34:35]
	v_rcp_f32_e32 v1, v1
	v_rcp_f32_e32 v6, v6
	v_rcp_f32_e32 v7, v7
	v_rcp_f32_e32 v8, v8
	v_lshl_add_u64 v[18:19], s[60:61], 0, v[18:19]
	v_lshl_add_u64 v[18:19], v[18:19], 0, v[146:147]
	global_store_dwordx4 v[18:19], v[10:13], off offset:1024
	s_waitcnt vmcnt(15)
	v_mov_b32_e32 v14, v224
	v_mov_b32_e32 v15, v225
	v_mov_b32_e32 v16, v226
	v_mov_b32_e32 v17, v227
	v_lshlrev_b32_e32 v9, 16, v14
	v_and_b32_e32 v10, 0xffff0000, v14
	v_lshlrev_b32_e32 v11, 16, v15
	v_and_b32_e32 v12, 0xffff0000, v15
	v_lshlrev_b32_e32 v13, 16, v16
	v_and_b32_e32 v14, 0xffff0000, v16
	v_lshlrev_b32_e32 v15, 16, v17
	v_and_b32_e32 v16, 0xffff0000, v17
	v_mul_f32_e32 v1, v1, v9
	v_mul_f32_e32 v9, v2, v13
	v_mul_f32_e32 v2, v6, v10
	v_mul_f32_e32 v6, v3, v14
	v_mul_f32_e32 v3, v7, v11
	v_mul_f32_e32 v7, v4, v15
	v_mul_f32_e32 v4, v8, v12
	v_mul_f32_e32 v5, v5, v16
	v_cvt_pk_bf16_f32 v2, v1, v2
	v_cvt_pk_bf16_f32 v3, v3, v4
	v_cvt_pk_bf16_f32 v4, v9, v6
	v_cvt_pk_bf16_f32 v5, v7, v5
	global_store_dwordx4 v[18:19], v[2:5], off offset:1280
	s_waitcnt vmcnt(0)
	s_barrier
	s_branch .LBB0_390
